# grid barrier: every workgroup waits on the XCD-leader arrival counter itself (>= (gen+1)*nx); the returning TOP atomic, the TOPGEN word and the per-XCD republish are gone; leader write-back and per-wo
# baseline (speedup 1.0000x reference)
.LBB0_71:
	s_or_b64 exec, exec, s[10:11]
	v_cvt_f32_u32_e32 v4, v2
	s_waitcnt vmcnt(0)
	v_readfirstlane_b32 s8, v3
	v_sub_u32_e32 v3, 0, v2
	v_rcp_iflag_f32_e32 v4, v4
	v_add_u32_e32 v5, s8, v1
	v_mul_f32_e32 v4, 0x4f7ffffe, v4
	v_cvt_u32_f32_e32 v4, v4
	v_mul_lo_u32 v1, v3, v4
	v_mul_hi_u32 v1, v4, v1
	v_add_u32_e32 v1, v4, v1
	v_mul_hi_u32 v1, v5, v1
	v_mul_lo_u32 v3, v1, v2
	v_sub_u32_e32 v3, v5, v3
	v_add_u32_e32 v4, 1, v1
	v_cmp_ge_u32_e32 vcc, v3, v2
	s_nop 1
	v_cndmask_b32_e32 v1, v1, v4, vcc
	v_sub_u32_e32 v4, v3, v2
	v_cndmask_b32_e32 v3, v3, v4, vcc
	v_add_u32_e32 v4, 1, v1
	v_cmp_ge_u32_e32 vcc, v3, v2
	v_add_u32_e32 v3, 1, v5
	s_nop 0
	v_cndmask_b32_e32 v1, v1, v4, vcc
	v_mul_lo_u32 v4, v2, v1
	v_add_u32_e32 v2, v4, v2
	v_add_u32_e32 v4, 1, v1
	v_mul_lo_u32 v4, v4, v0
	s_add_u32 s6, s4, 0x2f81400
	s_addc_u32 s7, s5, 0
	v_mov_b32_e32 v5, 0
	v_cmp_eq_u32_e32 vcc, v3, v2
	s_and_saveexec_b64 s[8:9], vcc
	s_cbranch_execz .Lxb0_poll
	buffer_wbl2 sc1
	s_waitcnt vmcnt(0) lgkmcnt(0)
	v_mov_b32_e32 v3, 1
	global_atomic_add v5, v3, s[6:7]

.Lxb0_spin:
	global_load_dword v3, v5, s[6:7] sc1
	s_waitcnt vmcnt(0)
	v_cmp_lt_u32_e32 vcc, v3, v4
	s_cbranch_vccz .Lxb0_done
	s_sleep 1
	s_branch .Lxb0_spin
.Lxb0_done:
	buffer_inv sc1
	s_waitcnt vmcnt(0)

.LBB0_177:
	s_or_b64 exec, exec, s[8:9]
	v_cvt_f32_u32_e32 v4, v2
	s_waitcnt vmcnt(0)
	v_readfirstlane_b32 s6, v3
	v_sub_u32_e32 v3, 0, v2
	v_rcp_iflag_f32_e32 v4, v4
	v_add_u32_e32 v5, s6, v1
	v_mul_f32_e32 v4, 0x4f7ffffe, v4
	v_cvt_u32_f32_e32 v4, v4
	v_mul_lo_u32 v1, v3, v4
	v_mul_hi_u32 v1, v4, v1
	v_add_u32_e32 v1, v4, v1
	v_mul_hi_u32 v1, v5, v1
	v_mul_lo_u32 v3, v1, v2
	v_sub_u32_e32 v3, v5, v3
	v_add_u32_e32 v4, 1, v1
	v_cmp_ge_u32_e32 vcc, v3, v2
	s_nop 1
	v_cndmask_b32_e32 v1, v1, v4, vcc
	v_sub_u32_e32 v4, v3, v2
	v_cndmask_b32_e32 v3, v3, v4, vcc
	v_add_u32_e32 v4, 1, v1
	v_cmp_ge_u32_e32 vcc, v3, v2
	v_add_u32_e32 v3, 1, v5
	s_nop 0
	v_cndmask_b32_e32 v1, v1, v4, vcc
	v_mul_lo_u32 v4, v2, v1
	v_add_u32_e32 v2, v4, v2
	v_add_u32_e32 v4, 1, v1
	v_mul_lo_u32 v4, v4, v0
	s_add_u32 s6, s2, 0x2f81400
	s_addc_u32 s7, s3, 0
	v_mov_b32_e32 v5, 0
	v_cmp_eq_u32_e32 vcc, v3, v2
	s_and_saveexec_b64 s[8:9], vcc
	s_cbranch_execz .Lxb1_poll
	buffer_wbl2 sc1
	s_waitcnt vmcnt(0) lgkmcnt(0)
	v_mov_b32_e32 v3, 1
	global_atomic_add v5, v3, s[6:7]

.LBB0_237:
	s_or_b64 exec, exec, s[10:11]
	v_cvt_f32_u32_e32 v4, v2
	s_waitcnt vmcnt(0)
	v_readfirstlane_b32 s8, v3
	v_sub_u32_e32 v3, 0, v2
	v_rcp_iflag_f32_e32 v4, v4
	v_add_u32_e32 v5, s8, v1
	v_mul_f32_e32 v4, 0x4f7ffffe, v4
	v_cvt_u32_f32_e32 v4, v4
	v_mul_lo_u32 v1, v3, v4
	v_mul_hi_u32 v1, v4, v1
	v_add_u32_e32 v1, v4, v1
	v_mul_hi_u32 v1, v5, v1
	v_mul_lo_u32 v3, v1, v2
	v_sub_u32_e32 v3, v5, v3
	v_add_u32_e32 v4, 1, v1
	v_cmp_ge_u32_e32 vcc, v3, v2
	s_nop 1
	v_cndmask_b32_e32 v1, v1, v4, vcc
	v_sub_u32_e32 v4, v3, v2
	v_cndmask_b32_e32 v3, v3, v4, vcc
	v_add_u32_e32 v4, 1, v1
	v_cmp_ge_u32_e32 vcc, v3, v2
	v_add_u32_e32 v3, 1, v5
	s_nop 0
	v_cndmask_b32_e32 v1, v1, v4, vcc
	v_mul_lo_u32 v4, v2, v1
	v_add_u32_e32 v2, v4, v2
	v_add_u32_e32 v4, 1, v1
	v_mul_lo_u32 v4, v4, v0
	s_add_u32 s6, s2, 0x2f81400
	s_addc_u32 s7, s3, 0
	v_mov_b32_e32 v5, 0
	v_cmp_eq_u32_e32 vcc, v3, v2
	s_and_saveexec_b64 s[8:9], vcc
	s_cbranch_execz .Lxb2_poll
	buffer_wbl2 sc1
	s_waitcnt vmcnt(0) lgkmcnt(0)
	v_mov_b32_e32 v3, 1
	global_atomic_add v5, v3, s[6:7]

.Lxb8_done:
	buffer_inv sc1
	s_waitcnt vmcnt(0)
	s_branch .Ltr_LBB0_108
